# grid barrier leader: XGEN release of the local workgroups issued before the leader's own L1 invalidate, no wait for the TOPGEN add ack in front of it (on top of the non-leader early invalidate)
# baseline (speedup 1.0000x reference)
.LBB0_68:
	s_or_b64 exec, exec, s[6:7]
	s_mov_b64 s[6:7], exec
	v_mbcnt_lo_u32_b32 v1, s6, 0
	v_mbcnt_hi_u32_b32 v1, s7, v1
	v_cmp_eq_u32_e32 vcc, 0, v1
	s_and_saveexec_b64 s[10:11], vcc
	s_cbranch_execz .LBB0_70
	s_bcnt1_i32_b64 s6, s[6:7]
	v_mov_b32_e32 v1, 0x2000
	v_mov_b32_e32 v2, s6
	global_atomic_add v1, v2, s[4:5] offset:1024
.LBB0_70:
	s_or_b64 exec, exec, s[10:11]
	buffer_inv sc1
	s_waitcnt vmcnt(0)

.LBB0_269:
	s_or_b64 exec, exec, s[6:7]
	s_mov_b64 s[6:7], exec
	v_mbcnt_lo_u32_b32 v1, s6, 0
	v_mbcnt_hi_u32_b32 v1, s7, v1
	v_cmp_eq_u32_e32 vcc, 0, v1
	s_and_saveexec_b64 s[8:9], vcc
	s_cbranch_execz .LBB0_271
	s_bcnt1_i32_b64 s6, s[6:7]
	v_mov_b32_e32 v1, 0x2000
	v_mov_b32_e32 v2, s6
	global_atomic_add v1, v2, s[4:5] offset:1024
.LBB0_271:
	s_or_b64 exec, exec, s[8:9]
	buffer_inv sc1
	s_waitcnt vmcnt(0)

.LBB0_607:
	s_or_b64 exec, exec, s[8:9]
	s_mov_b64 s[8:9], exec
	v_mbcnt_lo_u32_b32 v0, s8, 0
	v_mbcnt_hi_u32_b32 v0, s9, v0
	v_cmp_eq_u32_e32 vcc, 0, v0
	s_and_saveexec_b64 s[10:11], vcc
	s_cbranch_execz .LBB0_609
	s_bcnt1_i32_b64 s5, s[8:9]
	v_readlane_b32 s8, v253, 20
	v_mov_b32_e32 v0, s5
	v_readlane_b32 s9, v253, 21
	s_nop 4
	global_atomic_add v33, v0, s[8:9]
